# gemm_out first layer: the 17th panel of each XCD group computed by all 32 workgroups of the group (32 columns each, weights in LDS, A fragments streamed) instead of a fifth tile round on 8 workgroups
# speedup vs baseline: 1.0038x; 1.0038x over previous
.LBB0_1181:
	s_or_b64 exec, exec, s[76:77]
	s_cmp_lg_u64 s[90:91], 0
	s_cbranch_scc1 .Lgo_skip
	v_and_b32_e32 v37, 31, v143
	v_bfe_u32 v38, v143, 5, 1
	v_lshrrev_b32_e32 v32, 6, v143
	v_lshl_add_u32 v32, v32, 5, v37
	v_lshlrev_b32_e32 v32, 11, v32
	v_lshl_add_u32 v33, v38, 5, v32
	v_lshl_add_u32 v32, v38, 4, v32
	v_lshlrev_b32_e32 v34, 4, v143
	v_lshrrev_b32_e32 v35, 7, v143
	v_mul_u32_u24_e32 v35, 2064, v35
	v_and_b32_e32 v36, 127, v143
	v_lshl_add_u32 v35, v36, 4, v35
	v_mul_u32_u24_e32 v36, 2064, v37
	v_lshl_add_u32 v36, v38, 4, v36
	v_readlane_b32 s0, v253, 0
	s_and_b32 s1, s0, 7
	s_lshr_b32 s0, s0, 3
	s_mul_i32 s1, s1, 17
	s_add_u32 s1, s1, 16
	s_lshl_b32 s1, s1, 19
	s_lshl_b32 s12, s0, 16
	s_lshl_b32 s13, s74, 21
	s_add_u32 s12, s12, s13
	s_add_u32 s12, s12, 0xc40000
	s_add_u32 s4, s50, s12
	s_addc_u32 s5, s51, 0
	s_add_u32 s12, s1, 0x18bd000
	s_add_u32 s6, s50, s12
	s_addc_u32 s7, s51, 0
	s_lshl_b32 s0, s0, 6
	s_add_u32 s12, s1, s0
	s_add_u32 s12, s12, 0x108dd000
	s_add_u32 s8, s50, s12
	s_addc_u32 s9, s51, 0
	s_mov_b64 s[10:11], s[4:5]
	global_load_dwordx4 v[16:19], v34, s[10:11]
	s_add_u32 s10, s10, 0x2000
	s_addc_u32 s11, s11, 0
	global_load_dwordx4 v[20:23], v34, s[10:11]
	s_add_u32 s10, s10, 0x2000
	s_addc_u32 s11, s11, 0
	global_load_dwordx4 v[24:27], v34, s[10:11]
	s_add_u32 s10, s10, 0x2000
	s_addc_u32 s11, s11, 0
	global_load_dwordx4 v[28:31], v34, s[10:11]
	s_add_u32 s10, s10, 0x2000
	s_addc_u32 s11, s11, 0
	global_load_dwordx4 v[220:223], v34, s[10:11]
	s_add_u32 s10, s10, 0x2000
	s_addc_u32 s11, s11, 0
	global_load_dwordx4 v[224:227], v34, s[10:11]
	s_add_u32 s10, s10, 0x2000
	s_addc_u32 s11, s11, 0
	global_load_dwordx4 v[228:231], v34, s[10:11]
	s_add_u32 s10, s10, 0x2000
	s_addc_u32 s11, s11, 0
	global_load_dwordx4 v[240:243], v34, s[10:11]
	global_load_dwordx4 v[48:51], v32, s[6:7] offset:0
	global_load_dwordx4 v[52:55], v32, s[6:7] offset:32
	global_load_dwordx4 v[56:59], v32, s[6:7] offset:64
	global_load_dwordx4 v[60:63], v32, s[6:7] offset:96
	global_load_dwordx4 v[64:67], v32, s[6:7] offset:128
	global_load_dwordx4 v[68:71], v32, s[6:7] offset:160
	global_load_dwordx4 v[72:75], v32, s[6:7] offset:192
	global_load_dwordx4 v[76:79], v32, s[6:7] offset:224
	global_load_dwordx4 v[96:99], v32, s[6:7] offset:256
	global_load_dwordx4 v[100:103], v32, s[6:7] offset:288
	global_load_dwordx4 v[104:107], v32, s[6:7] offset:320
	global_load_dwordx4 v[108:111], v32, s[6:7] offset:352
	global_load_dwordx4 v[112:115], v32, s[6:7] offset:384
	global_load_dwordx4 v[116:119], v32, s[6:7] offset:416
	global_load_dwordx4 v[120:123], v32, s[6:7] offset:448
	global_load_dwordx4 v[124:127], v32, s[6:7] offset:480
	global_load_dwordx4 v[188:191], v32, s[6:7] offset:512
	global_load_dwordx4 v[192:195], v32, s[6:7] offset:544
	global_load_dwordx4 v[196:199], v32, s[6:7] offset:576
	global_load_dwordx4 v[200:203], v32, s[6:7] offset:608
	global_load_dwordx4 v[204:207], v32, s[6:7] offset:640
	global_load_dwordx4 v[208:211], v32, s[6:7] offset:672
	global_load_dwordx4 v[212:215], v32, s[6:7] offset:704
	global_load_dwordx4 v[216:219], v32, s[6:7] offset:736
	s_waitcnt vmcnt(24)
	ds_write_b128 v35, v[16:19] offset:0
	ds_write_b128 v35, v[20:23] offset:8256
	ds_write_b128 v35, v[24:27] offset:16512
	ds_write_b128 v35, v[28:31] offset:24768
	ds_write_b128 v35, v[220:223] offset:33024
	ds_write_b128 v35, v[224:227] offset:41280
	ds_write_b128 v35, v[228:231] offset:49536
	ds_write_b128 v35, v[240:243] offset:57792
	s_waitcnt lgkmcnt(0)
	s_barrier
	ds_read_b128 v[130:133], v36 offset:0
	ds_read_b128 v[134:137], v36 offset:32
	ds_read_b128 v[138:141], v36 offset:64
	ds_read_b128 v[144:147], v36 offset:96
	ds_read_b128 v[148:151], v36 offset:128
	ds_read_b128 v[152:155], v36 offset:160
	ds_read_b128 v[160:163], v36 offset:192
	ds_read_b128 v[164:167], v36 offset:224
	s_waitcnt vmcnt(23) lgkmcnt(7)
	v_mfma_f32_32x32x16_bf16 v[0:15], v[130:133], v[48:51], 0
	ds_read_b128 v[130:133], v36 offset:256
	global_load_dwordx4 v[48:51], v32, s[6:7] offset:768
	s_waitcnt vmcnt(23) lgkmcnt(7)
	v_mfma_f32_32x32x16_bf16 v[0:15], v[134:137], v[52:55], v[0:15]
	ds_read_b128 v[134:137], v36 offset:288
	global_load_dwordx4 v[52:55], v32, s[6:7] offset:800
	s_waitcnt vmcnt(23) lgkmcnt(7)
	v_mfma_f32_32x32x16_bf16 v[0:15], v[138:141], v[56:59], v[0:15]
	ds_read_b128 v[138:141], v36 offset:320
	global_load_dwordx4 v[56:59], v32, s[6:7] offset:832
	s_waitcnt vmcnt(23) lgkmcnt(7)
	v_mfma_f32_32x32x16_bf16 v[0:15], v[144:147], v[60:63], v[0:15]
	ds_read_b128 v[144:147], v36 offset:352
	global_load_dwordx4 v[60:63], v32, s[6:7] offset:864
	s_waitcnt vmcnt(23) lgkmcnt(7)
	v_mfma_f32_32x32x16_bf16 v[0:15], v[148:151], v[64:67], v[0:15]
	ds_read_b128 v[148:151], v36 offset:384
	global_load_dwordx4 v[64:67], v32, s[6:7] offset:896
	s_waitcnt vmcnt(23) lgkmcnt(7)
	v_mfma_f32_32x32x16_bf16 v[0:15], v[152:155], v[68:71], v[0:15]
	ds_read_b128 v[152:155], v36 offset:416
	global_load_dwordx4 v[68:71], v32, s[6:7] offset:928
	s_waitcnt vmcnt(23) lgkmcnt(7)
	v_mfma_f32_32x32x16_bf16 v[0:15], v[160:163], v[72:75], v[0:15]
	ds_read_b128 v[160:163], v36 offset:448
	global_load_dwordx4 v[72:75], v32, s[6:7] offset:960
	s_waitcnt vmcnt(23) lgkmcnt(7)
	v_mfma_f32_32x32x16_bf16 v[0:15], v[164:167], v[76:79], v[0:15]
	ds_read_b128 v[164:167], v36 offset:480
	global_load_dwordx4 v[76:79], v32, s[6:7] offset:992
	s_waitcnt vmcnt(23) lgkmcnt(7)
	v_mfma_f32_32x32x16_bf16 v[0:15], v[130:133], v[96:99], v[0:15]
	ds_read_b128 v[130:133], v36 offset:512
	global_load_dwordx4 v[96:99], v32, s[6:7] offset:1024
	s_waitcnt vmcnt(23) lgkmcnt(7)
	v_mfma_f32_32x32x16_bf16 v[0:15], v[134:137], v[100:103], v[0:15]
	ds_read_b128 v[134:137], v36 offset:544
	global_load_dwordx4 v[100:103], v32, s[6:7] offset:1056
	s_waitcnt vmcnt(23) lgkmcnt(7)
	v_mfma_f32_32x32x16_bf16 v[0:15], v[138:141], v[104:107], v[0:15]
	ds_read_b128 v[138:141], v36 offset:576
	global_load_dwordx4 v[104:107], v32, s[6:7] offset:1088
	s_waitcnt vmcnt(23) lgkmcnt(7)
	v_mfma_f32_32x32x16_bf16 v[0:15], v[144:147], v[108:111], v[0:15]
	ds_read_b128 v[144:147], v36 offset:608
	global_load_dwordx4 v[108:111], v32, s[6:7] offset:1120
	s_waitcnt vmcnt(23) lgkmcnt(7)
	v_mfma_f32_32x32x16_bf16 v[0:15], v[148:151], v[112:115], v[0:15]
	ds_read_b128 v[148:151], v36 offset:640
	global_load_dwordx4 v[112:115], v32, s[6:7] offset:1152
	s_waitcnt vmcnt(23) lgkmcnt(7)
	v_mfma_f32_32x32x16_bf16 v[0:15], v[152:155], v[116:119], v[0:15]
	ds_read_b128 v[152:155], v36 offset:672
	global_load_dwordx4 v[116:119], v32, s[6:7] offset:1184
	s_waitcnt vmcnt(23) lgkmcnt(7)
	v_mfma_f32_32x32x16_bf16 v[0:15], v[160:163], v[120:123], v[0:15]
	ds_read_b128 v[160:163], v36 offset:704
	global_load_dwordx4 v[120:123], v32, s[6:7] offset:1216
	s_waitcnt vmcnt(23) lgkmcnt(7)
	v_mfma_f32_32x32x16_bf16 v[0:15], v[164:167], v[124:127], v[0:15]
	ds_read_b128 v[164:167], v36 offset:736
	global_load_dwordx4 v[124:127], v32, s[6:7] offset:1248
	s_waitcnt vmcnt(23) lgkmcnt(7)
	v_mfma_f32_32x32x16_bf16 v[0:15], v[130:133], v[188:191], v[0:15]
	ds_read_b128 v[130:133], v36 offset:768
	global_load_dwordx4 v[188:191], v32, s[6:7] offset:1280
	s_waitcnt vmcnt(23) lgkmcnt(7)
	v_mfma_f32_32x32x16_bf16 v[0:15], v[134:137], v[192:195], v[0:15]
	ds_read_b128 v[134:137], v36 offset:800
	global_load_dwordx4 v[192:195], v32, s[6:7] offset:1312
	s_waitcnt vmcnt(23) lgkmcnt(7)
	v_mfma_f32_32x32x16_bf16 v[0:15], v[138:141], v[196:199], v[0:15]
	ds_read_b128 v[138:141], v36 offset:832
	global_load_dwordx4 v[196:199], v32, s[6:7] offset:1344
	s_waitcnt vmcnt(23) lgkmcnt(7)
	v_mfma_f32_32x32x16_bf16 v[0:15], v[144:147], v[200:203], v[0:15]
	ds_read_b128 v[144:147], v36 offset:864
	global_load_dwordx4 v[200:203], v32, s[6:7] offset:1376
	s_waitcnt vmcnt(23) lgkmcnt(7)
	v_mfma_f32_32x32x16_bf16 v[0:15], v[148:151], v[204:207], v[0:15]
	ds_read_b128 v[148:151], v36 offset:896
	global_load_dwordx4 v[204:207], v32, s[6:7] offset:1408
	s_waitcnt vmcnt(23) lgkmcnt(7)
	v_mfma_f32_32x32x16_bf16 v[0:15], v[152:155], v[208:211], v[0:15]
	ds_read_b128 v[152:155], v36 offset:928
	global_load_dwordx4 v[208:211], v32, s[6:7] offset:1440
	s_waitcnt vmcnt(23) lgkmcnt(7)
	v_mfma_f32_32x32x16_bf16 v[0:15], v[160:163], v[212:215], v[0:15]
	ds_read_b128 v[160:163], v36 offset:960
	global_load_dwordx4 v[212:215], v32, s[6:7] offset:1472
	s_waitcnt vmcnt(23) lgkmcnt(7)
	v_mfma_f32_32x32x16_bf16 v[0:15], v[164:167], v[216:219], v[0:15]
	ds_read_b128 v[164:167], v36 offset:992
	global_load_dwordx4 v[216:219], v32, s[6:7] offset:1504
	s_waitcnt vmcnt(23) lgkmcnt(7)
	v_mfma_f32_32x32x16_bf16 v[0:15], v[130:133], v[48:51], v[0:15]
	ds_read_b128 v[130:133], v36 offset:1024
	global_load_dwordx4 v[48:51], v32, s[6:7] offset:1536
	s_waitcnt vmcnt(23) lgkmcnt(7)
	v_mfma_f32_32x32x16_bf16 v[0:15], v[134:137], v[52:55], v[0:15]
	ds_read_b128 v[134:137], v36 offset:1056
	global_load_dwordx4 v[52:55], v32, s[6:7] offset:1568
	s_waitcnt vmcnt(23) lgkmcnt(7)
	v_mfma_f32_32x32x16_bf16 v[0:15], v[138:141], v[56:59], v[0:15]
	ds_read_b128 v[138:141], v36 offset:1088
	global_load_dwordx4 v[56:59], v32, s[6:7] offset:1600
	s_waitcnt vmcnt(23) lgkmcnt(7)
	v_mfma_f32_32x32x16_bf16 v[0:15], v[144:147], v[60:63], v[0:15]
	ds_read_b128 v[144:147], v36 offset:1120
	global_load_dwordx4 v[60:63], v32, s[6:7] offset:1632
	s_waitcnt vmcnt(23) lgkmcnt(7)
	v_mfma_f32_32x32x16_bf16 v[0:15], v[148:151], v[64:67], v[0:15]
	ds_read_b128 v[148:151], v36 offset:1152
	global_load_dwordx4 v[64:67], v32, s[6:7] offset:1664
	s_waitcnt vmcnt(23) lgkmcnt(7)
	v_mfma_f32_32x32x16_bf16 v[0:15], v[152:155], v[68:71], v[0:15]
	ds_read_b128 v[152:155], v36 offset:1184
	global_load_dwordx4 v[68:71], v32, s[6:7] offset:1696
	s_waitcnt vmcnt(23) lgkmcnt(7)
	v_mfma_f32_32x32x16_bf16 v[0:15], v[160:163], v[72:75], v[0:15]
	ds_read_b128 v[160:163], v36 offset:1216
	global_load_dwordx4 v[72:75], v32, s[6:7] offset:1728
	s_waitcnt vmcnt(23) lgkmcnt(7)
	v_mfma_f32_32x32x16_bf16 v[0:15], v[164:167], v[76:79], v[0:15]
	ds_read_b128 v[164:167], v36 offset:1248
	global_load_dwordx4 v[76:79], v32, s[6:7] offset:1760
	s_waitcnt vmcnt(23) lgkmcnt(7)
	v_mfma_f32_32x32x16_bf16 v[0:15], v[130:133], v[96:99], v[0:15]
	ds_read_b128 v[130:133], v36 offset:1280
	global_load_dwordx4 v[96:99], v32, s[6:7] offset:1792
	s_waitcnt vmcnt(23) lgkmcnt(7)
	v_mfma_f32_32x32x16_bf16 v[0:15], v[134:137], v[100:103], v[0:15]
	ds_read_b128 v[134:137], v36 offset:1312
	global_load_dwordx4 v[100:103], v32, s[6:7] offset:1824
	s_waitcnt vmcnt(23) lgkmcnt(7)
	v_mfma_f32_32x32x16_bf16 v[0:15], v[138:141], v[104:107], v[0:15]
	ds_read_b128 v[138:141], v36 offset:1344
	global_load_dwordx4 v[104:107], v32, s[6:7] offset:1856
	s_waitcnt vmcnt(23) lgkmcnt(7)
	v_mfma_f32_32x32x16_bf16 v[0:15], v[144:147], v[108:111], v[0:15]
	ds_read_b128 v[144:147], v36 offset:1376
	global_load_dwordx4 v[108:111], v32, s[6:7] offset:1888
	s_waitcnt vmcnt(23) lgkmcnt(7)
	v_mfma_f32_32x32x16_bf16 v[0:15], v[148:151], v[112:115], v[0:15]
	ds_read_b128 v[148:151], v36 offset:1408
	global_load_dwordx4 v[112:115], v32, s[6:7] offset:1920
	s_waitcnt vmcnt(23) lgkmcnt(7)
	v_mfma_f32_32x32x16_bf16 v[0:15], v[152:155], v[116:119], v[0:15]
	ds_read_b128 v[152:155], v36 offset:1440
	global_load_dwordx4 v[116:119], v32, s[6:7] offset:1952
	s_waitcnt vmcnt(23) lgkmcnt(7)
	v_mfma_f32_32x32x16_bf16 v[0:15], v[160:163], v[120:123], v[0:15]
	ds_read_b128 v[160:163], v36 offset:1472
	global_load_dwordx4 v[120:123], v32, s[6:7] offset:1984
	s_waitcnt vmcnt(23) lgkmcnt(7)
	v_mfma_f32_32x32x16_bf16 v[0:15], v[164:167], v[124:127], v[0:15]
	ds_read_b128 v[164:167], v36 offset:1504
	global_load_dwordx4 v[124:127], v32, s[6:7] offset:2016
	s_waitcnt vmcnt(23) lgkmcnt(7)
	v_mfma_f32_32x32x16_bf16 v[0:15], v[130:133], v[188:191], v[0:15]
	ds_read_b128 v[130:133], v36 offset:1536
	s_waitcnt vmcnt(22) lgkmcnt(7)
	v_mfma_f32_32x32x16_bf16 v[0:15], v[134:137], v[192:195], v[0:15]
	ds_read_b128 v[134:137], v36 offset:1568
	s_waitcnt vmcnt(21) lgkmcnt(7)
	v_mfma_f32_32x32x16_bf16 v[0:15], v[138:141], v[196:199], v[0:15]
	ds_read_b128 v[138:141], v36 offset:1600
	s_waitcnt vmcnt(20) lgkmcnt(7)
	v_mfma_f32_32x32x16_bf16 v[0:15], v[144:147], v[200:203], v[0:15]
	ds_read_b128 v[144:147], v36 offset:1632
	s_waitcnt vmcnt(19) lgkmcnt(7)
	v_mfma_f32_32x32x16_bf16 v[0:15], v[148:151], v[204:207], v[0:15]
	ds_read_b128 v[148:151], v36 offset:1664
	s_waitcnt vmcnt(18) lgkmcnt(7)
	v_mfma_f32_32x32x16_bf16 v[0:15], v[152:155], v[208:211], v[0:15]
	ds_read_b128 v[152:155], v36 offset:1696
	s_waitcnt vmcnt(17) lgkmcnt(7)
	v_mfma_f32_32x32x16_bf16 v[0:15], v[160:163], v[212:215], v[0:15]
	ds_read_b128 v[160:163], v36 offset:1728
	s_waitcnt vmcnt(16) lgkmcnt(7)
	v_mfma_f32_32x32x16_bf16 v[0:15], v[164:167], v[216:219], v[0:15]
	ds_read_b128 v[164:167], v36 offset:1760
	s_waitcnt vmcnt(15) lgkmcnt(7)
	v_mfma_f32_32x32x16_bf16 v[0:15], v[130:133], v[48:51], v[0:15]
	ds_read_b128 v[130:133], v36 offset:1792
	s_waitcnt vmcnt(14) lgkmcnt(7)
	v_mfma_f32_32x32x16_bf16 v[0:15], v[134:137], v[52:55], v[0:15]
	ds_read_b128 v[134:137], v36 offset:1824
	s_waitcnt vmcnt(13) lgkmcnt(7)
	v_mfma_f32_32x32x16_bf16 v[0:15], v[138:141], v[56:59], v[0:15]
	ds_read_b128 v[138:141], v36 offset:1856
	s_waitcnt vmcnt(12) lgkmcnt(7)
	v_mfma_f32_32x32x16_bf16 v[0:15], v[144:147], v[60:63], v[0:15]
	ds_read_b128 v[144:147], v36 offset:1888
	s_waitcnt vmcnt(11) lgkmcnt(7)
	v_mfma_f32_32x32x16_bf16 v[0:15], v[148:151], v[64:67], v[0:15]
	ds_read_b128 v[148:151], v36 offset:1920
	s_waitcnt vmcnt(10) lgkmcnt(7)
	v_mfma_f32_32x32x16_bf16 v[0:15], v[152:155], v[68:71], v[0:15]
	ds_read_b128 v[152:155], v36 offset:1952
	s_waitcnt vmcnt(9) lgkmcnt(7)
	v_mfma_f32_32x32x16_bf16 v[0:15], v[160:163], v[72:75], v[0:15]
	ds_read_b128 v[160:163], v36 offset:1984
	s_waitcnt vmcnt(8) lgkmcnt(7)
	v_mfma_f32_32x32x16_bf16 v[0:15], v[164:167], v[76:79], v[0:15]
	ds_read_b128 v[164:167], v36 offset:2016
	s_waitcnt vmcnt(7) lgkmcnt(7)
	v_mfma_f32_32x32x16_bf16 v[0:15], v[130:133], v[96:99], v[0:15]
	s_waitcnt vmcnt(6) lgkmcnt(6)
	v_mfma_f32_32x32x16_bf16 v[0:15], v[134:137], v[100:103], v[0:15]
	s_waitcnt vmcnt(5) lgkmcnt(5)
	v_mfma_f32_32x32x16_bf16 v[0:15], v[138:141], v[104:107], v[0:15]
	s_waitcnt vmcnt(4) lgkmcnt(4)
	v_mfma_f32_32x32x16_bf16 v[0:15], v[144:147], v[108:111], v[0:15]
	s_waitcnt vmcnt(3) lgkmcnt(3)
	v_mfma_f32_32x32x16_bf16 v[0:15], v[148:151], v[112:115], v[0:15]
	s_waitcnt vmcnt(2) lgkmcnt(2)
	v_mfma_f32_32x32x16_bf16 v[0:15], v[152:155], v[116:119], v[0:15]
	s_waitcnt vmcnt(1) lgkmcnt(1)
	v_mfma_f32_32x32x16_bf16 v[0:15], v[160:163], v[120:123], v[0:15]
	s_waitcnt vmcnt(0) lgkmcnt(0)
	v_mfma_f32_32x32x16_bf16 v[0:15], v[164:167], v[124:127], v[0:15]
	s_nop 7
	s_nop 7
	v_cvt_pk_bf16_f32 v244, v0, v1
	v_cvt_pk_bf16_f32 v245, v2, v3
	v_cvt_pk_bf16_f32 v248, v4, v5
	v_cvt_pk_bf16_f32 v249, v6, v7
	v_cvt_pk_bf16_f32 v246, v8, v9
	v_cvt_pk_bf16_f32 v247, v10, v11
	v_cvt_pk_bf16_f32 v250, v12, v13
	v_cvt_pk_bf16_f32 v251, v14, v15
	s_nop 1
	v_permlane32_swap_b32_e32 v244, v246
	v_permlane32_swap_b32_e32 v245, v247
	v_permlane32_swap_b32_e32 v248, v250
	v_permlane32_swap_b32_e32 v249, v251
	global_store_dwordx4 v33, v[244:247], s[8:9]
	global_store_dwordx4 v33, v[248:251], s[8:9] offset:16
	s_waitcnt vmcnt(0)
	s_barrier
.Lgo_skip:
	v_mov_b32_e32 v0, v143
	s_and_b64 vcc, exec, s[72:73]
	s_cbranch_vccz .LBB0_1183
	v_readlane_b32 s6, v255, 23
	s_mov_b32 s1, 0
	s_mov_b32 s0, 0
	v_readlane_b32 s4, v253, 0
	v_readlane_b32 s7, v255, 24
	s_mov_b32 s5, s6
	s_branch .LBB0_1184

.LBB0_1184:
	s_and_b64 s[6:7], s[90:91], exec
	s_movk_i32 s6, 0x80
	s_cselect_b32 s6, s6, 0x88
	s_and_b32 s1, 0xffff, s1
	s_lshr_b32 s1, s6, s1
	s_lshl_b32 s6, s1, 3
	s_min_u32 s6, s6, 0x80
	s_cmp_ge_i32 s4, s6
	s_mov_b32 s13, 0x20000
	s_cbranch_scc1 .LBB0_1191
	v_ashrrev_i32_e32 v1, 6, v0
	v_lshrrev_b32_e32 v3, 31, v0
	s_mul_i32 s7, s0, s1
	s_lshl_b32 s0, s74, 21
	v_readlane_b32 s1, v253, 56
	v_add_u32_e32 v3, v1, v3
	s_add_u32 s0, s1, s0
	v_readlane_b32 s1, v253, 57
	v_ashrrev_i32_e32 v4, 1, v3
	v_and_b32_e32 v5, 7, v0
	v_and_b32_e32 v3, 0x3ffffe, v3
	s_addc_u32 s1, s1, 0
	v_and_b32_e32 v2, 31, v0
	v_sub_u32_e32 v3, v1, v3
	v_lshlrev_b32_e32 v128, 4, v5
	v_lshlrev_b32_e32 v97, 6, v4
	v_ashrrev_i32_e32 v96, 3, v0
	v_bfe_u32 v7, v0, 5, 1
	v_lshl_add_u64 v[82:83], s[0:1], 0, v[128:129]
	s_movk_i32 s0, 0x90
	v_or_b32_e32 v9, v97, v2
	v_lshl_or_b32 v3, v3, 6, v2
	v_mul_lo_u32 v8, v96, s0
	v_mul_lo_u32 v9, v9, s0
	v_lshlrev_b32_e32 v10, 4, v7
	v_mul_lo_u32 v3, v3, s0
	v_readlane_b32 s0, v255, 20
	v_add3_u32 v98, 0, v9, v10
	v_add_u32_e32 v9, 0, v3
	v_add_u32_e32 v12, s0, v8
	v_add_u32_e32 v3, s0, v3
	s_movk_i32 s0, 0x1200
	v_mul_lo_u32 v1, v1, s0
	v_bfe_u32 v100, v0, 3, 3
	v_lshlrev_b32_e32 v6, 3, v5
	v_readlane_b32 s8, v253, 38
	v_add_u32_e32 v99, 0, v8
	v_readlane_b32 s1, v255, 21
	v_add_u32_e32 v1, 0, v1
	v_or_b32_e32 v101, 8, v100
	s_movk_i32 s0, 0xffc0
	v_readlane_b32 s9, v253, 39
	v_add_u32_e32 v5, 0, v128
	v_add_u32_e32 v11, 0xd800, v99
	v_add_u32_e32 v13, s1, v8
	v_lshl_add_u32 v2, v2, 1, v1
	v_add_u32_e32 v1, v1, v128
	v_mul_u32_u24_e32 v14, 0x90, v100
	v_mul_u32_u24_e32 v7, 0x240, v7
	v_mul_u32_u24_e32 v15, 0x90, v101
	v_and_or_b32 v0, v0, s0, v6
	v_lshlrev_b32_e32 v4, 7, v4
	v_mov_b32_e32 v64, 0
	v_lshl_add_u64 v[80:81], s[8:9], 0, v[128:129]
	v_or_b32_e32 v102, 16, v100
	v_or_b32_e32 v103, 24, v100
	v_sub_u32_e32 v104, v0, v4
	s_lshl_b32 s8, s4, 7
	s_lshl_b32 s9, s5, 7
	s_mov_b64 s[0:1], 0
	v_add_u32_e32 v105, v5, v8
	v_add_u32_e32 v106, v9, v10
	v_add_u32_e32 v107, v11, v128
	v_add_u32_e32 v108, v12, v128
	v_add_u32_e32 v109, v13, v128
	v_add_u32_e32 v110, v3, v10
	v_add_u32_e32 v111, v2, v7
	v_add_u32_e32 v112, v1, v14
	v_add_u32_e32 v113, v1, v15
	v_mov_b32_e32 v65, v64
	v_mov_b32_e32 v66, v64
	v_mov_b32_e32 v67, v64
	v_mov_b32_e32 v68, v64
	v_mov_b32_e32 v69, v64
	v_mov_b32_e32 v70, v64
	v_mov_b32_e32 v71, v64
	v_mov_b32_e32 v72, v64
	v_mov_b32_e32 v73, v64
	v_mov_b32_e32 v74, v64
	v_mov_b32_e32 v75, v64
	v_mov_b32_e32 v76, v64
	v_mov_b32_e32 v77, v64
	v_mov_b32_e32 v78, v64
	v_mov_b32_e32 v79, v64
	s_branch .LBB0_1187
